# conv_a2 A2 loop: the two mu vector loads requested together with the z taps (one round trip per item instead of two)
# speedup vs baseline: 1.0047x; 1.0047x over previous
.LBB0_659:
	s_or_b64 exec, exec, s[12:13]
	v_readlane_b32 s8, v254, 52
	v_readlane_b32 s9, v254, 53
	s_nop 1
	v_lshl_add_u64 v[122:123], v[16:17], 2, s[8:9]
	global_load_dwordx4 v[114:117], v[122:123], off
	global_load_dwordx4 v[118:121], v[122:123], off offset:16
	s_waitcnt vmcnt(0)
	v_cvt_f32_f16_e32 v15, v4
	s_movk_i32 s1, 0xffd0
	v_mad_u64_u32 v[20:21], s[10:11], v13, s1, v[14:15]
	v_cmp_lt_i32_e64 s[38:39], 15, v20
	v_cmp_gt_u32_e32 vcc, 32, v20
	v_cvt_f32_f16_e32 v13, v8
	v_add_f32_e32 v13, v15, v13
	v_fma_mix_f32 v13, v13, s76, -v0 op_sel_hi:[0,0,1]
	s_waitcnt vmcnt(0)
	v_mov_b32_e32 v22, v114
	v_fma_mix_f32 v15, v22, v13, v0 op_sel_hi:[0,0,1]
	s_and_saveexec_b64 s[10:11], s[38:39]
	s_xor_b64 s[12:13], exec, s[10:11]
	s_cbranch_execz .LBB0_661
	v_mul_f32_e32 v13, 0xbfb8aa3b, v15
	v_exp_f32_e32 v13, v13
	s_nop 0
	v_add_f32_e32 v13, 1.0, v13
	v_rcp_f32_e32 v13, v13
	s_nop 0
	v_cndmask_b32_e32 v13, v13, v15, vcc
